# HGRN second pass: all unit-prologue loads issued up front (state, gates, first step), on top of combo
# baseline (speedup 1.0000x reference)
; #define LAS __attribute__((address_space(3)))
; __device__ __forceinline__ unsigned pk2(float lo, float hi) { f32x2_t v = {lo, hi}; bf16x2_t b = __builtin_convertvector(v, bf16x2_t); return __builtin_bit_cast(unsigned, b); }
; template <bool PC> __device__ __forceinline__ void hgrn_unit(LAS unsigned char* lds, int unit, const bf16* P0, const float* lbp, const float* ong, float* Lst, const float* Sst, float* Dtot, bf16* MIX) {
;     ...
;     f32x4 S[8];
;     if (PC) {
; #pragma unroll
;         for (int kb = 0; kb < 8; ++kb) { S[kb] = *(const f32x4*)(Sst + (size_t)unit * 16384 + (16 * kb + li) * 128 + 16 * wave + 4 * g);
;             *(LAS v2u*)(lds + HL_S + (16 * kb + li) * RS + (16 * wave + 4 * g) * 2) = (v2u){pk2(S[kb][0], S[kb][1]), pk2(S[kb][2], S[kb][3])}; }
;     } else {
; #pragma unroll
;         for (int kb = 0; kb < 8; ++kb) S[kb] = (f32x4){0.f, 0.f, 0.f, 0.f};
;     }
;     float sumlog = 0.f;
;     f32x4 g0 = (f32x4){0.f, 0.f, 0.f, 0.f}, g1 = g0; if (PC) { g0 = *(const f32x4*)(ong + hd * 128 + 8 * (tid & 15)); g1 = *(const f32x4*)(ong + hd * 128 + 8 * (tid & 15) + 4); }
;     LAS float* DEC = (LAS float*)(lds + HL_DEC);
;     unsigned nf[8], nq[8]; v4u nv, ng = (v4u){0u, 0u, 0u, 0u};
.LBB0_458:
	v_mov_b32_e32 v61, v216
	s_lshl_b32 s14, s58, 8
	v_ashrrev_i32_e32 v63, 6, v61
	v_and_b32_e32 v68, 15, v61
	s_and_b32 s18, s14, 0x1f00
	v_lshlrev_b32_e32 v44, 4, v63
	s_lshl_b32 s14, s58, 2
	v_or_b32_e32 v46, v44, v68
	s_and_b32 s17, s14, 0x180
	v_add_u32_e32 v0, s17, v46
	s_ashr_i32 s59, s58, 31
	s_and_b32 s5, s84, 0xffffe000
	s_and_b32 s16, s86, 0x1f00
	s_lshl_b32 s0, s58, 6
	v_ashrrev_i32_e32 v1, 31, v0
	s_lshl_b64 s[14:15], s[58:59], 16
	v_lshl_add_u64 v[20:21], v[0:1], 2, s[78:79]
	v_add_u32_e32 v0, 0x400, v0
	s_add_u32 s14, s80, s14
	v_bfe_u32 v69, v61, 4, 2
	v_ashrrev_i32_e32 v1, 31, v0
	s_addc_u32 s15, s81, s15
	v_ashrrev_i32_e32 v45, 31, v44
	v_lshl_add_u64 v[22:23], v[0:1], 2, s[78:79]
	v_lshl_add_u64 v[0:1], v[44:45], 2, s[14:15]
	v_lshlrev_b32_e32 v56, 4, v69
	v_lshlrev_b32_e32 v30, 9, v68
	v_or_b32_e32 v45, 32, v68
	v_lshl_add_u64 v[28:29], v[0:1], 0, v[56:57]
	v_mov_b32_e32 v31, v57
	v_or_b32_e32 v2, 0x2000, v30
	v_mov_b32_e32 v3, v57
	v_lshlrev_b32_e32 v8, 9, v45
	v_mov_b32_e32 v9, v57
	v_or_b32_e32 v10, 0x6000, v30
	v_mov_b32_e32 v11, v57
	v_or_b32_e32 v16, 0x8000, v30
	v_mov_b32_e32 v17, v57
	v_lshl_add_u64 v[0:1], v[28:29], 0, v[30:31]
	v_lshl_add_u64 v[2:3], v[28:29], 0, v[2:3]
	v_lshl_add_u64 v[8:9], v[28:29], 0, v[8:9]
	v_lshl_add_u64 v[10:11], v[28:29], 0, v[10:11]
	v_lshl_add_u64 v[16:17], v[28:29], 0, v[16:17]
	global_load_dwordx4 v[4:7], v[0:1], off
	s_nop 0
	global_load_dwordx4 v[0:3], v[2:3], off
	s_nop 0
	global_load_dwordx4 v[12:15], v[8:9], off
	s_nop 0
	global_load_dwordx4 v[8:11], v[10:11], off
	s_nop 0
	global_load_dwordx4 v[16:19], v[16:17], off
	s_nop 0
	global_load_dword v42, v[20:21], off
	global_load_dword v43, v[20:21], off offset:2048
	global_load_dword v47, v[22:23], off
	v_or_b32_e32 v20, 0xa000, v30
	v_mov_b32_e32 v21, v57
	v_lshl_add_u64 v[20:21], v[28:29], 0, v[20:21]
	v_or_b32_e32 v24, 0xc000, v30
	v_mov_b32_e32 v25, v57
	global_load_dwordx4 v[20:23], v[20:21], off
	v_lshl_add_u64 v[24:25], v[28:29], 0, v[24:25]
	v_or_b32_e32 v30, 0xe000, v30
	global_load_dwordx4 v[24:27], v[24:25], off
	v_lshl_add_u64 v[28:29], v[28:29], 0, v[30:31]
	global_load_dwordx4 v[28:31], v[28:29], off
	v_lshlrev_b32_e32 v70, 2, v69
	v_or_b32_e32 v32, v70, v44
	v_lshl_add_u32 v48, v32, 1, 0
	v_mad_u32_u24 v49, v68, s88, v48
	v_mad_u32_u24 v104, v68, s88, v96
	v_mad_u32_u24 v105, v68, s88, v97
	v_add_u32_e32 v50, v48, v104
	v_mad_u32_u24 v106, v68, s88, v98
	s_and_b32 s0, s0, 0xffffe000
	s_or_b32 s18, s0, s18
	s_lshl_b32 s0, s17, 2
	s_add_u32 s14, s82, s0
	s_waitcnt vmcnt(26)
	v_lshlrev_b32_e32 v73, 3, v69
	s_addc_u32 s15, s83, 0
	s_lshl_b32 s0, s17, 1
	s_waitcnt vmcnt(25)
	v_ashrrev_i32_e32 v74, 4, v61
	v_lshl_add_u32 v72, v46, 1, 0
	v_bfe_u32 v71, v61, 2, 2
	v_add_u32_e32 v112, 0, v56
	v_lshlrev_b32_e32 v66, 3, v68
	v_or_b32_e32 v121, 32, v73
	v_cmp_gt_i32_e64 s[44:45], 4, v63
	v_mul_u32_u24_e32 v103, 0x110, v68
	v_mul_u32_u24_e32 v45, 0x50, v45
	v_cmp_eq_u32_e64 s[38:39], 0, v69
	v_cmp_lt_u32_e64 s[40:41], 1, v69
	v_cmp_eq_u32_e64 s[42:43], 3, v69
	v_cmp_gt_u32_e64 s[50:51], v70, v68
	v_cmp_lt_u32_e64 s[52:53], v70, v68
	v_lshl_add_u32 v131, v121, 1, 0
	v_lshl_add_u32 v118, v68, 2, 0
	v_add_u32_e32 v131, v131, v103
	v_lshlrev_b32_e32 v140, 5, v68
	v_or_b32_e32 v142, s18, v73
	global_load_dwordx4 v[144:147], v140, s[14:15]
	global_load_dwordx4 v[148:151], v140, s[14:15] offset:16
	v_mad_i64_i32 v[142:143], s[100:101], v142, s90, v[58:59]
	v_mov_b32_e32 v152, v46
	v_ashrrev_i32_e32 v153, 31, v46
	v_lshl_add_u64 v[142:143], v[142:143], 0, s[0:1]
	v_lshlrev_b64 v[152:153], 1, v[152:153]
	v_lshl_add_u64 v[142:143], v[142:143], 0, v[152:153]
	global_load_ushort v86, v[142:143], off
	global_load_ushort v93, v[142:143], off offset:1024
	s_mov_b64 s[98:99], 0x1000
	v_lshl_add_u64 v[154:155], v[142:143], 0, s[98:99]
	global_load_ushort v87, v[154:155], off offset:2048
	global_load_ushort v92, v[154:155], off offset:3072
	s_mov_b64 s[98:99], 0x3000
	v_lshl_add_u64 v[154:155], v[142:143], 0, s[98:99]
	global_load_ushort v84, v[154:155], off
	global_load_ushort v89, v[154:155], off offset:1024
	s_mov_b64 s[98:99], 0x4000
	v_lshl_add_u64 v[154:155], v[142:143], 0, s[98:99]
	global_load_ushort v85, v[154:155], off offset:2048
	global_load_ushort v88, v[154:155], off offset:3072
	s_mov_b64 s[98:99], 0x6000
	v_lshl_add_u64 v[154:155], v[142:143], 0, s[98:99]
	global_load_ushort v82, v[154:155], off
	global_load_ushort v91, v[154:155], off offset:1024
	s_mov_b64 s[98:99], 0x7000
	v_lshl_add_u64 v[154:155], v[142:143], 0, s[98:99]
	global_load_ushort v83, v[154:155], off offset:2048
	global_load_ushort v90, v[154:155], off offset:3072
	s_mov_b64 s[98:99], 0x9000
	v_lshl_add_u64 v[154:155], v[142:143], 0, s[98:99]
	global_load_ushort v80, v[154:155], off
	global_load_ushort v95, v[154:155], off offset:1024
	s_mov_b64 s[98:99], 0xa000
	v_lshl_add_u64 v[154:155], v[142:143], 0, s[98:99]
	global_load_ushort v81, v[154:155], off offset:2048
	global_load_ushort v94, v[154:155], off offset:3072
	v_add_u32_e32 v156, s18, v74
	v_mad_i64_i32 v[156:157], s[100:101], v156, s90, v[58:59]
	v_lshlrev_b32_e32 v158, 4, v68
	v_mov_b32_e32 v159, v57
	v_lshl_add_u64 v[156:157], v[156:157], 0, s[0:1]
	v_lshl_add_u64 v[156:157], v[156:157], 0, v[158:159]
	global_load_dwordx4 v[160:163], v[156:157], off offset:2048
	global_load_dwordx4 v[164:167], v[156:157], off offset:3072
	s_waitcnt vmcnt(30)
	v_cvt_pk_bf16_f32 v32, v4, v5
	v_cvt_pk_bf16_f32 v33, v6, v7
	s_waitcnt vmcnt(29)
	v_cvt_pk_bf16_f32 v34, v0, v1
	s_waitcnt vmcnt(23)
; #define LAS __attribute__((address_space(3)))
; __device__ __forceinline__ unsigned pk2(float lo, float hi) { f32x2_t v = {lo, hi}; bf16x2_t b = __builtin_convertvector(v, bf16x2_t); return __builtin_bit_cast(unsigned, b); }
; template <bool PC> __device__ __forceinline__ void hgrn_unit(LAS unsigned char* lds, int unit, const bf16* P0, const float* lbp, const float* ong, float* Lst, const float* Sst, float* Dtot, bf16* MIX) {
;     ...
;     { const float a0 = lbp[hd * 128 + k], a1 = lbp[512 + hd * 128 + k], a2 = lbp[1024 + hd * 128 + k]; const float mx = fmaxf(a0, fmaxf(a1, a2));
;       const float e0 = __expf(a0 - mx), e1 = __expf(a1 - mx), e2 = __expf(a2 - mx); lb = e0 / (e0 + e1 + e2); }
;     f32x4 S[8];
;     if (PC) {
; #pragma unroll
;         for (int kb = 0; kb < 8; ++kb) { S[kb] = *(const f32x4*)(Sst + (size_t)unit * 16384 + (16 * kb + li) * 128 + 16 * wave + 4 * g);
;             *(LAS v2u*)(lds + HL_S + (16 * kb + li) * RS + (16 * wave + 4 * g) * 2) = (v2u){pk2(S[kb][0], S[kb][1]), pk2(S[kb][2], S[kb][3])}; }
	v_max3_f32 v51, v42, v43, v47
	v_cvt_pk_bf16_f32 v35, v2, v3
	ds_write_b64 v49, v[32:33] offset:58368
	ds_write_b64 v49, v[34:35] offset:62720
	v_sub_f32_e32 v32, v42, v51
	v_sub_f32_e32 v33, v43, v51
	v_sub_f32_e32 v34, v47, v51
	v_mul_f32_e32 v32, 0x3fb8aa3b, v32
	v_mul_f32_e32 v33, 0x3fb8aa3b, v33
	v_mul_f32_e32 v34, 0x3fb8aa3b, v34
	v_exp_f32_e32 v54, v32
	v_exp_f32_e32 v32, v33
	v_exp_f32_e32 v33, v34
	v_cvt_pk_bf16_f32 v36, v12, v13
	v_cvt_pk_bf16_f32 v37, v14, v15
	v_add_f32_e32 v32, v54, v32
	v_cvt_pk_bf16_f32 v40, v16, v17
	v_cvt_pk_bf16_f32 v41, v18, v19
	v_add_f32_e32 v55, v33, v32
	v_add_u32_e32 v34, v48, v105
	s_waitcnt vmcnt(22)
	v_cvt_pk_bf16_f32 v32, v20, v21
	v_cvt_pk_bf16_f32 v33, v22, v23
	v_cvt_pk_bf16_f32 v38, v8, v9
	v_cvt_pk_bf16_f32 v39, v10, v11
	ds_write_b64 v50, v[36:37] offset:58368
	ds_write_b64 v50, v[38:39] offset:62720
	ds_write_b64 v34, v[40:41] offset:58368
	ds_write_b64 v34, v[32:33] offset:62720
	s_waitcnt vmcnt(21)
	v_cvt_pk_bf16_f32 v32, v24, v25
	v_cvt_pk_bf16_f32 v33, v26, v27
	v_add_u32_e32 v34, v48, v106
	ds_write_b64 v34, v[32:33] offset:58368
	s_waitcnt vmcnt(20)
; #define LAS __attribute__((address_space(3)))
; template <bool PC> __device__ __forceinline__ void hgrn_unit(LAS unsigned char* lds, int unit, const bf16* P0, const float* lbp, const float* ong, float* Lst, const float* Sst, float* Dtot, bf16* MIX) {
;     ...
;     f32x4 g0 = (f32x4){0.f, 0.f, 0.f, 0.f}, g1 = g0; if (PC) { g0 = *(const f32x4*)(ong + hd * 128 + 8 * (tid & 15)); g1 = *(const f32x4*)(ong + hd * 128 + 8 * (tid & 15) + 4); }
;     LAS float* DEC = (LAS float*)(lds + HL_DEC);
;     unsigned nf[8], nq[8]; v4u nv, ng = (v4u){0u, 0u, 0u, 0u};
	v_cvt_pk_bf16_f32 v32, v28, v29
	v_cvt_pk_bf16_f32 v33, v30, v31
	ds_write_b64 v34, v[32:33] offset:62720
	v_lshlrev_b32_e32 v36, 5, v68
	v_or_b32_e32 v40, s18, v73
	s_nop 0
	v_mad_i64_i32 v[40:41], s[14:15], v40, s90, v[58:59]
	v_ashrrev_i32_e32 v47, 31, v46
	v_lshl_add_u64 v[40:41], v[40:41], 0, s[0:1]
	v_lshlrev_b64 v[48:49], 1, v[46:47]
	v_lshl_add_u64 v[40:41], v[40:41], 0, v[48:49]
	s_movk_i32 s14, 0x1000
	v_add_co_u32_e32 v42, vcc, s14, v40
	s_movk_i32 s14, 0x3000
	s_nop 0
	v_addc_co_u32_e32 v43, vcc, 0, v41, vcc
	v_add_co_u32_e32 v50, vcc, s14, v40
	s_movk_i32 s14, 0x4000
	s_nop 0
	v_addc_co_u32_e32 v51, vcc, 0, v41, vcc
	v_add_co_u32_e32 v52, vcc, s14, v40
	s_movk_i32 s14, 0x7000
	s_nop 0
	v_addc_co_u32_e32 v53, vcc, 0, v41, vcc
	v_add_co_u32_e32 v42, vcc, s89, v40
	v_addc_co_u32_e32 v43, vcc, 0, v41, vcc
	v_add_co_u32_e32 v50, vcc, s14, v40
	s_mov_b32 s14, 0x9000
	s_nop 0
	v_addc_co_u32_e32 v51, vcc, 0, v41, vcc
	v_add_co_u32_e32 v52, vcc, s14, v40
	s_mov_b32 s14, 0xa000
	s_nop 0
	v_addc_co_u32_e32 v53, vcc, 0, v41, vcc
	v_add_co_u32_e32 v40, vcc, s14, v40
	v_div_scale_f32 v47, s[14:15], v55, v55, v54
	v_rcp_f32_e32 v60, v47
	v_addc_co_u32_e32 v41, vcc, 0, v41, vcc
	v_fma_f32 v40, -v47, v60, 1.0
	v_fmac_f32_e32 v60, v40, v60
	v_div_scale_f32 v40, vcc, v54, v55, v54
	v_mul_f32_e32 v41, v40, v60
	v_fma_f32 v42, -v47, v41, v40
	v_fmac_f32_e32 v41, v42, v60
	v_fma_f32 v40, -v47, v41, v40
	v_div_fmas_f32 v40, v40, v60, v41
	v_div_fixup_f32 v60, v40, v55, v54
	v_add_u32_e32 v40, s18, v74
	v_mad_i64_i32 v[40:41], s[14:15], v40, s90, v[58:59]
	v_lshl_add_u64 v[40:41], v[40:41], 0, s[0:1]
	v_lshlrev_b32_e32 v50, 4, v68
	v_mov_b32_e32 v51, v57
	v_lshl_add_u64 v[40:41], v[40:41], 0, v[50:51]
	s_nop 0
	v_mul_lo_u32 v47, v74, s88
	v_cmp_lt_i32_e32 vcc, v100, v217
	v_add_u32_e32 v75, 0, v47
	s_movk_i32 s14, 0x4e
	v_cndmask_b32_e32 v47, v100, v208, vcc
	v_cmp_lt_i32_e32 vcc, v101, v217
	v_lshlrev_b32_e32 v107, 2, v47
	v_mad_u64_u32 v[64:65], s[14:15], v46, s14, v[72:73]
	v_cndmask_b32_e32 v47, v101, v208, vcc
	v_cmp_lt_i32_e32 vcc, v102, v217
	v_lshlrev_b32_e32 v108, 2, v47
	s_movk_i32 s14, 0xffb4
	v_cndmask_b32_e32 v47, v102, v208, vcc
	v_cmp_lt_i32_e32 vcc, v211, v209
	v_lshlrev_b32_e32 v109, 2, v47
	v_mul_lo_u32 v76, v46, s14
	v_cndmask_b32_e32 v47, v208, v211, vcc
	v_cmp_lt_i32_e32 vcc, v210, v209
	v_lshlrev_b32_e32 v110, 2, v47
	v_ashrrev_i32_e32 v46, 7, v61
	v_cndmask_b32_e32 v47, v208, v210, vcc
	v_lshlrev_b32_e32 v111, 2, v47
	v_and_b32_e32 v47, 1, v63
	v_lshl_or_b32 v65, v47, 4, v68
	v_lshl_or_b32 v67, v46, 4, v68
	v_mad_u32_u24 v77, v65, s88, 0
	v_mul_lo_u32 v65, v67, s88
	s_movk_i32 s14, 0xff40
	v_cmp_le_i32_e64 s[46:47], v47, v46
	v_add_u32_e32 v65, 0, v65
	v_cmp_eq_u32_e64 s[48:49], v47, v46
	v_mul_lo_u32 v46, v67, s14
	v_lshlrev_b32_e32 v47, 5, v47
	v_add3_u32 v78, v65, v46, v47
	v_or_b32_e32 v46, v73, v71
	v_mul_u32_u24_e32 v79, 0x110, v46
	v_mad_u32_u24 v127, v46, s88, 0
	v_lshlrev_b32_e32 v46, 2, v61
	v_and_or_b32 v46, v46, 12, v44
	v_lshlrev_b32_e32 v128, 1, v46
	v_sub_u32_e32 v46, v112, v73
	s_movk_i32 s14, 0x84
	v_lshl_add_u32 v113, v63, 5, v46
	v_mul_lo_u32 v46, v74, s14
	v_cmp_lt_i32_e32 vcc, v215, v209
	v_add_lshl_u32 v138, v46, v66, 2
	v_or_b32_e32 v61, v121, v71
	v_cndmask_b32_e32 v46, v208, v215, vcc
	v_cmp_lt_i32_e32 vcc, v214, v209
	v_lshlrev_b32_e32 v114, 2, v46
	v_mul_u32_u24_e32 v130, 0x110, v61
	v_cndmask_b32_e32 v46, v208, v214, vcc
	v_cmp_lt_i32_e32 vcc, v213, v209
	v_lshlrev_b32_e32 v115, 2, v46
	v_or_b32_e32 v61, 64, v73
	v_cndmask_b32_e32 v46, v208, v213, vcc
	v_cmp_lt_i32_e32 vcc, v212, v209
	v_lshlrev_b32_e32 v116, 2, v46
	v_mov_b32_e32 v47, v57
	v_cndmask_b32_e32 v46, v208, v212, vcc
	v_lshlrev_b32_e32 v117, 2, v46
	v_or_b32_e32 v46, s17, v66
	v_lshlrev_b32_e32 v46, 1, v46
	v_or_b32_e32 v63, v61, v71
	v_lshl_add_u32 v133, v61, 1, 0
	v_or_b32_e32 v61, 0x60, v73
	v_lshl_add_u64 v[66:67], s[2:3], 0, v[46:47]
	v_or_b32_e32 v47, 2, v70
	v_mul_u32_u24_e32 v132, 0x110, v63
	v_or_b32_e32 v63, v61, v71
	v_lshl_add_u32 v136, v61, 1, 0
	v_mul_u32_u24_e32 v61, 0x84, v68
	v_cmp_gt_u32_e64 s[54:55], v47, v68
	v_or_b32_e32 v47, 3, v70
	v_add_lshl_u32 v119, v61, v44, 2
	s_add_u32 s14, s20, s0
	v_add_u32_e32 v134, 0, v128
	v_mul_u32_u24_e32 v46, 0x880, v69
	v_cmp_gt_u32_e64 s[56:57], v47, v68
	v_mul_u32_u24_e32 v47, 0x50, v68
	v_mul_u32_u24_e32 v135, 0x110, v63
	v_add_u32_e32 v44, 0x2100, v119
	s_addc_u32 s15, s21, 0
	v_sub_f32_e32 v62, 1.0, v60
	v_lshl_add_u64 v[68:69], s[14:15], 0, v[48:49]
	v_lshl_add_u64 v[70:71], s[14:15], 0, v[50:51]
	s_or_b32 s0, s5, s16
	v_add_u32_e32 v122, v75, v50
	v_add_u32_e32 v123, v72, v46
	v_add_u32_e32 v127, v127, v128
	v_add_u32_e32 v128, v112, v47
	v_add_u32_e32 v129, v134, v79
	v_add_u32_e32 v130, v134, v130
	v_add_u32_e32 v132, v134, v132
	v_add_u32_e32 v134, v134, v135
	v_add_u32_e32 v135, v136, v103
	v_add_u32_e32 v136, v112, v45
	v_add_u32_e32 v137, v112, v44
	s_waitcnt vmcnt(0)
	v_mov_b32_e32 v139, v93
	v_mov_b64_e32 v[32:33], v[144:145]
	v_mov_b64_e32 v[34:35], v[146:147]
	v_mov_b64_e32 v[36:37], v[148:149]
	v_mov_b64_e32 v[38:39], v[150:151]
	v_mov_b64_e32 v[52:53], v[160:161]
	v_mov_b64_e32 v[54:55], v[162:163]
	v_mov_b64_e32 v[40:41], v[164:165]
	v_mov_b64_e32 v[42:43], v[166:167]
	v_mov_b64_e32 v[46:47], v[42:43]
	v_mov_b64_e32 v[48:49], v[52:53]
	v_mov_b32_e32 v61, v60
	v_mov_b32_e32 v63, v62
	v_add_u32_e32 v120, s0, v74
	v_or_b32_e32 v121, s0, v121
	v_add_u32_e32 v124, v64, v76
	v_add_u32_e32 v125, v77, v56
	v_add_u32_e32 v126, v78, v73
	v_add_u32_e32 v133, v133, v103
	v_add_u32_e32 v138, 0, v138
	s_mov_b32 s0, 0
	v_mov_b32_e32 v140, v92
	v_mov_b32_e32 v141, v89
	v_mov_b32_e32 v142, v88
	v_mov_b32_e32 v143, v91
	v_mov_b32_e32 v144, v90
	v_mov_b32_e32 v145, v95
	v_mov_b32_e32 v146, v94
	v_mov_b64_e32 v[44:45], v[40:41]
	v_mov_b64_e32 v[50:51], v[54:55]
	v_mov_b64_e32 v[74:75], v[86:87]
	v_mov_b64_e32 v[72:73], v[84:85]
	v_mov_b64_e32 v[78:79], v[82:83]
	v_mov_b64_e32 v[76:77], v[80:81]
	s_branch .LBB0_462
